# v71 + in-proj K loop: after an epilogue the next tile's first two counted waits leave the epilogue's own stores outstanding (they only need data issued before those stores)
# speedup vs baseline: 1.0034x; 1.0034x over previous
.LBB0_1250:
	s_mov_b32 s100, 0
	v_mov_b32_e32 v4, v202
	v_cndmask_b32_e64 v2, 0, 1, s[64:65]
	s_movk_i32 s8, 0x400
	v_readfirstlane_b32 s17, v4
	s_movk_i32 s69, 0x400
	s_movk_i32 s9, 0x400
	v_cmp_ne_u32_e64 s[38:39], 1, v2
	s_andn2_b64 vcc, exec, s[64:65]
	s_cbranch_vccnz .LBB0_1252
	s_ashr_i32 s5, s36, 4
	s_and_b32 s5, s5, -2
	s_and_b32 s4, s36, 3
	s_add_i32 s6, s5, 14
	s_cmp_lt_u32 s4, 2
	s_cselect_b32 s5, s5, s6
	s_add_i32 s44, s5, s4
	s_bfe_u32 s80, s36, 0x30002
	s_mov_b64 s[4:5], -1
	s_cbranch_execz .LBB0_1253
	s_branch .LBB0_1255

.LBB0_1276:
	s_add_i32 s4, s63, 0x80
	s_cmp_eq_u32 s94, s65
	s_cselect_b32 s42, s45, s4
	s_cselect_b32 s40, s62, s64
	s_add_i32 s5, 0, 0x10000
	v_add_u32_e32 v2, s5, v190
	v_add_u32_e32 v136, s5, v191
	ds_read_b128 v[132:135], v2
	ds_read_b128 v[136:139], v136
	v_add_u32_e32 v2, s35, v190
	v_add_u32_e32 v144, s35, v191
	s_add_i32 s43, 0, 0x14000
	ds_read_b128 v[140:143], v2
	ds_read_b128 v[144:147], v144
	v_add_u32_e32 v2, s43, v190
	v_add_u32_e32 v152, s43, v191
	ds_read_b128 v[148:151], v2
	ds_read_b128 v[152:155], v152
	v_add_u32_e32 v2, s12, v190
	v_add_u32_e32 v160, s12, v191
	ds_read_b128 v[156:159], v2
	ds_read_b128 v[160:163], v160
	s_add_i32 s4, s42, 0x80
	s_add_i32 s20, s93, s63
	v_lshl_add_u64 v[194:195], v[182:183], 0, s[20:21]
	s_add_i32 m0, s86, 0xc000
	s_add_i32 s20, s69, s63
	ds_read_b128 v[164:167], v192
	ds_read_b128 v[168:171], v192 offset:2048
	ds_read_b128 v[172:175], v193
	ds_read_b128 v[176:179], v193 offset:2048
	ds_read_b128 v[184:187], v192 offset:4096
	ds_read_b128 v[220:223], v192 offset:6144
	ds_read_b128 v[224:227], v193 offset:4096
	ds_read_b128 v[228:231], v193 offset:6144
	global_load_lds_dwordx4 v[194:195], off
	v_lshl_add_u64 v[194:195], v[182:183], 0, s[20:21]
	s_add_i32 m0, s86, 0xe000
	s_nop 0
	global_load_lds_dwordx4 v[194:195], off
	s_cmp_lg_u32 s100, 0
	s_cbranch_scc1 .Llen1_x
	s_waitcnt vmcnt(8)
.Llen1_d:
	s_waitcnt lgkmcnt(0)
	s_barrier
	s_setprio 1
	s_waitcnt lgkmcnt(0)
	v_mfma_f32_16x16x32_bf16 v[128:131], v[132:135], v[164:167], v[128:131]
	v_mfma_f32_16x16x32_bf16 v[124:127], v[140:143], v[164:167], v[124:127]
	v_mfma_f32_16x16x32_bf16 v[112:115], v[132:135], v[168:171], v[112:115]
	v_mfma_f32_16x16x32_bf16 v[108:111], v[140:143], v[168:171], v[108:111]
	v_mfma_f32_16x16x32_bf16 v[96:99], v[132:135], v[184:187], v[96:99]
	v_mfma_f32_16x16x32_bf16 v[92:95], v[140:143], v[184:187], v[92:95]
	v_mfma_f32_16x16x32_bf16 v[80:83], v[132:135], v[220:223], v[80:83]
	v_mfma_f32_16x16x32_bf16 v[76:79], v[140:143], v[220:223], v[76:79]
	v_mfma_f32_16x16x32_bf16 v[128:131], v[136:139], v[172:175], v[128:131]
	v_mfma_f32_16x16x32_bf16 v[124:127], v[144:147], v[172:175], v[124:127]
	v_mfma_f32_16x16x32_bf16 v[112:115], v[136:139], v[176:179], v[112:115]
	v_mfma_f32_16x16x32_bf16 v[108:111], v[144:147], v[176:179], v[108:111]
	v_mfma_f32_16x16x32_bf16 v[96:99], v[136:139], v[224:227], v[96:99]
	v_mfma_f32_16x16x32_bf16 v[92:95], v[144:147], v[224:227], v[92:95]
	v_mfma_f32_16x16x32_bf16 v[80:83], v[136:139], v[228:231], v[80:83]
	v_mfma_f32_16x16x32_bf16 v[76:79], v[144:147], v[228:231], v[76:79]
	s_setprio 0
	s_setprio 1
	v_mfma_f32_16x16x32_bf16 v[120:123], v[148:151], v[164:167], v[120:123]
	v_mfma_f32_16x16x32_bf16 v[116:119], v[156:159], v[164:167], v[116:119]
	v_mfma_f32_16x16x32_bf16 v[104:107], v[148:151], v[168:171], v[104:107]
	v_mfma_f32_16x16x32_bf16 v[100:103], v[156:159], v[168:171], v[100:103]
	v_mfma_f32_16x16x32_bf16 v[88:91], v[148:151], v[184:187], v[88:91]
	v_mfma_f32_16x16x32_bf16 v[84:87], v[156:159], v[184:187], v[84:87]
	v_mfma_f32_16x16x32_bf16 v[72:75], v[148:151], v[220:223], v[72:75]
	v_mfma_f32_16x16x32_bf16 v[68:71], v[156:159], v[220:223], v[68:71]
	v_mfma_f32_16x16x32_bf16 v[120:123], v[152:155], v[172:175], v[120:123]
	v_mfma_f32_16x16x32_bf16 v[116:119], v[160:163], v[172:175], v[116:119]
	v_mfma_f32_16x16x32_bf16 v[104:107], v[152:155], v[176:179], v[104:107]
	v_mfma_f32_16x16x32_bf16 v[100:103], v[160:163], v[176:179], v[100:103]
	v_mfma_f32_16x16x32_bf16 v[88:91], v[152:155], v[224:227], v[88:91]
	v_mfma_f32_16x16x32_bf16 v[84:87], v[160:163], v[224:227], v[84:87]
	v_mfma_f32_16x16x32_bf16 v[72:75], v[152:155], v[228:231], v[72:75]
	v_mfma_f32_16x16x32_bf16 v[68:71], v[160:163], v[228:231], v[68:71]
	s_setprio 0
	s_barrier
	s_mov_b32 s41, s21
	s_add_i32 s5, s5, s85
	v_lshl_add_u64 v[194:195], v[180:181], 0, s[40:41]
	s_mov_b32 m0, s5
	s_add_i32 s20, s40, s84
	ds_read_b128 v[164:167], v192 offset:16384
	ds_read_b128 v[168:171], v192 offset:18432
	ds_read_b128 v[172:175], v193 offset:16384
	ds_read_b128 v[176:179], v193 offset:18432
	ds_read_b128 v[184:187], v192 offset:20480
	ds_read_b128 v[220:223], v192 offset:22528
	ds_read_b128 v[224:227], v193 offset:20480
	ds_read_b128 v[228:231], v193 offset:22528
	global_load_lds_dwordx4 v[194:195], off
	v_lshl_add_u64 v[194:195], v[180:181], 0, s[20:21]
	s_add_i32 m0, s5, 0x2000
	s_add_i32 s20, s20, s84
	s_add_i32 s5, s43, s85
	global_load_lds_dwordx4 v[194:195], off
	v_lshl_add_u64 v[194:195], v[180:181], 0, s[20:21]
	s_mov_b32 m0, s5
	s_add_i32 s20, s20, s84
	global_load_lds_dwordx4 v[194:195], off
	v_lshl_add_u64 v[194:195], v[180:181], 0, s[20:21]
	s_add_i32 m0, s5, 0x2000
	s_mov_b32 s43, s21
	global_load_lds_dwordx4 v[194:195], off
	v_lshl_add_u64 v[194:195], v[182:183], 0, s[42:43]
	s_mov_b32 m0, s86
	s_add_i32 s20, s42, s83
	global_load_lds_dwordx4 v[194:195], off
	v_lshl_add_u64 v[194:195], v[182:183], 0, s[20:21]
	s_mov_b32 m0, s87
	s_nop 0
	global_load_lds_dwordx4 v[194:195], off
	s_cmp_lg_u32 s100, 0
	s_cbranch_scc1 .Llen2_x
	s_waitcnt vmcnt(8)
.Llen2_d:
	s_waitcnt lgkmcnt(0)
	s_barrier
	s_setprio 1
	s_waitcnt lgkmcnt(0)
	v_mfma_f32_16x16x32_bf16 v[64:67], v[132:135], v[164:167], v[64:67]
	v_mfma_f32_16x16x32_bf16 v[60:63], v[140:143], v[164:167], v[60:63]
	v_mfma_f32_16x16x32_bf16 v[48:51], v[132:135], v[168:171], v[48:51]
	v_mfma_f32_16x16x32_bf16 v[44:47], v[140:143], v[168:171], v[44:47]
	v_mfma_f32_16x16x32_bf16 v[32:35], v[132:135], v[184:187], v[32:35]
	v_mfma_f32_16x16x32_bf16 v[28:31], v[140:143], v[184:187], v[28:31]
	v_mfma_f32_16x16x32_bf16 v[16:19], v[132:135], v[220:223], v[16:19]
	v_mfma_f32_16x16x32_bf16 v[12:15], v[140:143], v[220:223], v[12:15]
	v_mfma_f32_16x16x32_bf16 v[64:67], v[136:139], v[172:175], v[64:67]
	v_mfma_f32_16x16x32_bf16 v[60:63], v[144:147], v[172:175], v[60:63]
	v_mfma_f32_16x16x32_bf16 v[48:51], v[136:139], v[176:179], v[48:51]
	v_mfma_f32_16x16x32_bf16 v[44:47], v[144:147], v[176:179], v[44:47]
	v_mfma_f32_16x16x32_bf16 v[32:35], v[136:139], v[224:227], v[32:35]
	v_mfma_f32_16x16x32_bf16 v[28:31], v[144:147], v[224:227], v[28:31]
	v_mfma_f32_16x16x32_bf16 v[16:19], v[136:139], v[228:231], v[16:19]
	v_mfma_f32_16x16x32_bf16 v[12:15], v[144:147], v[228:231], v[12:15]
	s_setprio 0
	s_setprio 1
	v_mfma_f32_16x16x32_bf16 v[56:59], v[148:151], v[164:167], v[56:59]
	v_mfma_f32_16x16x32_bf16 v[52:55], v[156:159], v[164:167], v[52:55]
	v_mfma_f32_16x16x32_bf16 v[40:43], v[148:151], v[168:171], v[40:43]
	v_mfma_f32_16x16x32_bf16 v[36:39], v[156:159], v[168:171], v[36:39]
	v_mfma_f32_16x16x32_bf16 v[24:27], v[148:151], v[184:187], v[24:27]
	v_mfma_f32_16x16x32_bf16 v[20:23], v[156:159], v[184:187], v[20:23]
	v_mfma_f32_16x16x32_bf16 v[8:11], v[148:151], v[220:223], v[8:11]
	v_mfma_f32_16x16x32_bf16 v[4:7], v[156:159], v[220:223], v[4:7]
	v_mfma_f32_16x16x32_bf16 v[56:59], v[152:155], v[172:175], v[56:59]
	v_mfma_f32_16x16x32_bf16 v[52:55], v[160:163], v[172:175], v[52:55]
	v_mfma_f32_16x16x32_bf16 v[40:43], v[152:155], v[176:179], v[40:43]
	v_mfma_f32_16x16x32_bf16 v[36:39], v[160:163], v[176:179], v[36:39]
	v_mfma_f32_16x16x32_bf16 v[24:27], v[152:155], v[224:227], v[24:27]
	v_mfma_f32_16x16x32_bf16 v[20:23], v[160:163], v[224:227], v[20:23]
	v_mfma_f32_16x16x32_bf16 v[8:11], v[152:155], v[228:231], v[8:11]
	v_mfma_f32_16x16x32_bf16 v[4:7], v[160:163], v[228:231], v[4:7]
	s_setprio 0
	s_barrier
	s_add_i32 s5, 0, 0x18000
	v_add_u32_e32 v2, s5, v190
	v_add_u32_e32 v136, s5, v191
	ds_read_b128 v[132:135], v2
	ds_read_b128 v[136:139], v136
	v_add_u32_e32 v2, s13, v190
	v_add_u32_e32 v144, s13, v191
	s_add_i32 s41, 0, 0x1c000
	ds_read_b128 v[140:143], v2
	ds_read_b128 v[144:147], v144
	v_add_u32_e32 v2, s41, v190
	v_add_u32_e32 v152, s41, v191
	ds_read_b128 v[148:151], v2
	ds_read_b128 v[152:155], v152
	v_add_u32_e32 v2, s14, v190
	v_add_u32_e32 v160, s14, v191
	ds_read_b128 v[156:159], v2
	ds_read_b128 v[160:163], v160
	s_add_i32 s20, s20, s83
	s_mov_b32 m0, s88
	v_lshl_add_u64 v[194:195], v[182:183], 0, s[20:21]
	s_add_i32 s20, s20, s83
	ds_read_b128 v[164:167], v192 offset:32768
	ds_read_b128 v[168:171], v192 offset:34816
	ds_read_b128 v[172:175], v193 offset:32768
	ds_read_b128 v[176:179], v193 offset:34816
	ds_read_b128 v[184:187], v192 offset:36864
	ds_read_b128 v[220:223], v192 offset:38912
	ds_read_b128 v[224:227], v193 offset:36864
	ds_read_b128 v[228:231], v193 offset:38912
	global_load_lds_dwordx4 v[194:195], off
	v_lshl_add_u64 v[194:195], v[182:183], 0, s[20:21]
	s_mov_b32 m0, s89
	s_nop 0
	global_load_lds_dwordx4 v[194:195], off
	s_waitcnt vmcnt(8)
	s_waitcnt lgkmcnt(0)
	s_barrier
	s_setprio 1
	s_waitcnt lgkmcnt(0)
	v_mfma_f32_16x16x32_bf16 v[128:131], v[132:135], v[164:167], v[128:131]
	v_mfma_f32_16x16x32_bf16 v[124:127], v[140:143], v[164:167], v[124:127]
	v_mfma_f32_16x16x32_bf16 v[112:115], v[132:135], v[168:171], v[112:115]
	v_mfma_f32_16x16x32_bf16 v[108:111], v[140:143], v[168:171], v[108:111]
	v_mfma_f32_16x16x32_bf16 v[96:99], v[132:135], v[184:187], v[96:99]
	v_mfma_f32_16x16x32_bf16 v[92:95], v[140:143], v[184:187], v[92:95]
	v_mfma_f32_16x16x32_bf16 v[80:83], v[132:135], v[220:223], v[80:83]
	v_mfma_f32_16x16x32_bf16 v[76:79], v[140:143], v[220:223], v[76:79]
	v_mfma_f32_16x16x32_bf16 v[128:131], v[136:139], v[172:175], v[128:131]
	v_mfma_f32_16x16x32_bf16 v[124:127], v[144:147], v[172:175], v[124:127]
	v_mfma_f32_16x16x32_bf16 v[112:115], v[136:139], v[176:179], v[112:115]
	v_mfma_f32_16x16x32_bf16 v[108:111], v[144:147], v[176:179], v[108:111]
	v_mfma_f32_16x16x32_bf16 v[96:99], v[136:139], v[224:227], v[96:99]
	v_mfma_f32_16x16x32_bf16 v[92:95], v[144:147], v[224:227], v[92:95]
	v_mfma_f32_16x16x32_bf16 v[80:83], v[136:139], v[228:231], v[80:83]
	v_mfma_f32_16x16x32_bf16 v[76:79], v[144:147], v[228:231], v[76:79]
	s_setprio 0
	s_setprio 1
	v_mfma_f32_16x16x32_bf16 v[120:123], v[148:151], v[164:167], v[120:123]
	v_mfma_f32_16x16x32_bf16 v[116:119], v[156:159], v[164:167], v[116:119]
	v_mfma_f32_16x16x32_bf16 v[104:107], v[148:151], v[168:171], v[104:107]
	v_mfma_f32_16x16x32_bf16 v[100:103], v[156:159], v[168:171], v[100:103]
	v_mfma_f32_16x16x32_bf16 v[88:91], v[148:151], v[184:187], v[88:91]
	v_mfma_f32_16x16x32_bf16 v[84:87], v[156:159], v[184:187], v[84:87]
	v_mfma_f32_16x16x32_bf16 v[72:75], v[148:151], v[220:223], v[72:75]
	v_mfma_f32_16x16x32_bf16 v[68:71], v[156:159], v[220:223], v[68:71]
	v_mfma_f32_16x16x32_bf16 v[120:123], v[152:155], v[172:175], v[120:123]
	v_mfma_f32_16x16x32_bf16 v[116:119], v[160:163], v[172:175], v[116:119]
	v_mfma_f32_16x16x32_bf16 v[104:107], v[152:155], v[176:179], v[104:107]
	v_mfma_f32_16x16x32_bf16 v[100:103], v[160:163], v[176:179], v[100:103]
	v_mfma_f32_16x16x32_bf16 v[88:91], v[152:155], v[224:227], v[88:91]
	v_mfma_f32_16x16x32_bf16 v[84:87], v[160:163], v[224:227], v[84:87]
	v_mfma_f32_16x16x32_bf16 v[72:75], v[152:155], v[228:231], v[72:75]
	v_mfma_f32_16x16x32_bf16 v[68:71], v[160:163], v[228:231], v[68:71]
	s_setprio 0
	s_barrier
	s_add_i32 s20, s40, 0x80
	s_add_i32 s5, s5, s85
	v_lshl_add_u64 v[194:195], v[180:181], 0, s[20:21]
	s_mov_b32 m0, s5
	s_add_i32 s20, s20, s84
	ds_read_b128 v[164:167], v192 offset:49152
	ds_read_b128 v[168:171], v192 offset:51200
	ds_read_b128 v[172:175], v193 offset:49152
	ds_read_b128 v[176:179], v193 offset:51200
	ds_read_b128 v[184:187], v192 offset:53248
	ds_read_b128 v[220:223], v192 offset:55296
	ds_read_b128 v[224:227], v193 offset:53248
	ds_read_b128 v[228:231], v193 offset:55296
	global_load_lds_dwordx4 v[194:195], off
	v_lshl_add_u64 v[194:195], v[180:181], 0, s[20:21]
	s_add_i32 m0, s5, 0x2000
	s_add_i32 s20, s20, s84
	s_add_i32 s5, s41, s85
	global_load_lds_dwordx4 v[194:195], off
	v_lshl_add_u64 v[194:195], v[180:181], 0, s[20:21]
	s_mov_b32 m0, s5
	s_add_i32 s20, s20, s84
	global_load_lds_dwordx4 v[194:195], off
	v_lshl_add_u64 v[194:195], v[180:181], 0, s[20:21]
	s_add_i32 m0, s5, 0x2000
	s_mov_b32 s5, s21
	global_load_lds_dwordx4 v[194:195], off
	v_lshl_add_u64 v[194:195], v[182:183], 0, s[4:5]
	s_mov_b32 m0, s90
	s_add_i32 s20, s4, s83
	global_load_lds_dwordx4 v[194:195], off
	v_lshl_add_u64 v[194:195], v[182:183], 0, s[20:21]
	s_mov_b32 m0, s91
	s_nop 0
	global_load_lds_dwordx4 v[194:195], off
	s_waitcnt vmcnt(8)
	s_waitcnt lgkmcnt(0)
	s_barrier
	s_setprio 1
	s_waitcnt lgkmcnt(0)
	v_mfma_f32_16x16x32_bf16 v[64:67], v[132:135], v[164:167], v[64:67]
	v_mfma_f32_16x16x32_bf16 v[60:63], v[140:143], v[164:167], v[60:63]
	v_mfma_f32_16x16x32_bf16 v[48:51], v[132:135], v[168:171], v[48:51]
	v_mfma_f32_16x16x32_bf16 v[44:47], v[140:143], v[168:171], v[44:47]
	v_mfma_f32_16x16x32_bf16 v[32:35], v[132:135], v[184:187], v[32:35]
	v_mfma_f32_16x16x32_bf16 v[28:31], v[140:143], v[184:187], v[28:31]
	v_mfma_f32_16x16x32_bf16 v[16:19], v[132:135], v[220:223], v[16:19]
	v_mfma_f32_16x16x32_bf16 v[12:15], v[140:143], v[220:223], v[12:15]
	v_mfma_f32_16x16x32_bf16 v[64:67], v[136:139], v[172:175], v[64:67]
	v_mfma_f32_16x16x32_bf16 v[60:63], v[144:147], v[172:175], v[60:63]
	v_mfma_f32_16x16x32_bf16 v[48:51], v[136:139], v[176:179], v[48:51]
	v_mfma_f32_16x16x32_bf16 v[44:47], v[144:147], v[176:179], v[44:47]
	v_mfma_f32_16x16x32_bf16 v[32:35], v[136:139], v[224:227], v[32:35]
	v_mfma_f32_16x16x32_bf16 v[28:31], v[144:147], v[224:227], v[28:31]
	v_mfma_f32_16x16x32_bf16 v[16:19], v[136:139], v[228:231], v[16:19]
	v_mfma_f32_16x16x32_bf16 v[12:15], v[144:147], v[228:231], v[12:15]
	s_setprio 0
	s_setprio 1
	v_mfma_f32_16x16x32_bf16 v[56:59], v[148:151], v[164:167], v[56:59]
	v_mfma_f32_16x16x32_bf16 v[52:55], v[156:159], v[164:167], v[52:55]
	v_mfma_f32_16x16x32_bf16 v[40:43], v[148:151], v[168:171], v[40:43]
	v_mfma_f32_16x16x32_bf16 v[36:39], v[156:159], v[168:171], v[36:39]
	v_mfma_f32_16x16x32_bf16 v[24:27], v[148:151], v[184:187], v[24:27]
	v_mfma_f32_16x16x32_bf16 v[20:23], v[156:159], v[184:187], v[20:23]
	v_mfma_f32_16x16x32_bf16 v[8:11], v[148:151], v[220:223], v[8:11]
	v_mfma_f32_16x16x32_bf16 v[4:7], v[156:159], v[220:223], v[4:7]
	v_mfma_f32_16x16x32_bf16 v[56:59], v[152:155], v[172:175], v[56:59]
	v_mfma_f32_16x16x32_bf16 v[52:55], v[160:163], v[172:175], v[52:55]
	v_mfma_f32_16x16x32_bf16 v[40:43], v[152:155], v[176:179], v[40:43]
	v_mfma_f32_16x16x32_bf16 v[36:39], v[160:163], v[176:179], v[36:39]
	v_mfma_f32_16x16x32_bf16 v[24:27], v[152:155], v[224:227], v[24:27]
	v_mfma_f32_16x16x32_bf16 v[20:23], v[160:163], v[224:227], v[20:23]
	v_mfma_f32_16x16x32_bf16 v[8:11], v[152:155], v[228:231], v[8:11]
	v_mfma_f32_16x16x32_bf16 v[4:7], v[160:163], v[228:231], v[4:7]
	s_setprio 0
	s_barrier
	s_add_i32 s65, s65, 2
	s_addk_i32 s63, 0x100
	s_addk_i32 s64, 0x100
	s_cmp_ge_i32 s65, s92
	s_cbranch_scc0 .LBB0_1276

.LBB0_1537:
.LBB0_1538:
	s_cmp_gt_i32 s80, 10
	s_cselect_b32 s100, 1, 2
	s_andn2_b64 vcc, exec, s[74:75]
	s_mov_b64 s[4:5], -1
	s_cbranch_vccnz .LBB0_1263

.Llen1_x:
	s_cmp_eq_u32 s100, 1
	s_cbranch_scc1 .Llen1_g
	s_waitcnt vmcnt(24)
	s_branch .Llen1_d
.Llen1_g:
	s_waitcnt vmcnt(16)
	s_branch .Llen1_d
.Llen2_x:
	s_cmp_eq_u32 s100, 1
	s_cbranch_scc1 .Llen2_g
	s_waitcnt vmcnt(24)
	s_mov_b32 s100, 0
	s_branch .Llen2_d
.Llen2_g:
	s_waitcnt vmcnt(16)
	s_mov_b32 s100, 0
	s_branch .Llen2_d

	.amdhsa_kernel _Z10hybrid_fwd4Args
		.amdhsa_group_segment_fixed_size 0
		.amdhsa_private_segment_fixed_size 0
		.amdhsa_kernarg_size 432
		.amdhsa_user_sgpr_count 2
		.amdhsa_user_sgpr_dispatch_ptr 0
		.amdhsa_user_sgpr_queue_ptr 0
		.amdhsa_user_sgpr_kernarg_segment_ptr 1
		.amdhsa_user_sgpr_dispatch_id 0
		.amdhsa_user_sgpr_kernarg_preload_length 0
		.amdhsa_user_sgpr_kernarg_preload_offset 0
		.amdhsa_user_sgpr_private_segment_size 0
		.amdhsa_uses_dynamic_stack 0
		.amdhsa_enable_private_segment 0
		.amdhsa_system_sgpr_workgroup_id_x 1
		.amdhsa_system_sgpr_workgroup_id_y 0
		.amdhsa_system_sgpr_workgroup_id_z 0
		.amdhsa_system_sgpr_workgroup_info 0
		.amdhsa_system_vgpr_workitem_id 0
		.amdhsa_next_free_vgpr 256
		.amdhsa_next_free_sgpr 102
		.amdhsa_accum_offset 256
		.amdhsa_reserve_vcc 1
		.amdhsa_float_round_mode_32 0
		.amdhsa_float_round_mode_16_64 0
		.amdhsa_float_denorm_mode_32 3
		.amdhsa_float_denorm_mode_16_64 3
		.amdhsa_dx10_clamp 1
		.amdhsa_ieee_mode 1
		.amdhsa_fp16_overflow 0
		.amdhsa_tg_split 0
		.amdhsa_exception_fp_ieee_invalid_op 0
		.amdhsa_exception_fp_denorm_src 0
		.amdhsa_exception_fp_ieee_div_zero 0
		.amdhsa_exception_fp_ieee_overflow 0
		.amdhsa_exception_fp_ieee_underflow 0
		.amdhsa_exception_fp_ieee_inexact 0
		.amdhsa_exception_int_div_zero 0
	.end_amdhsa_kernel

amdhsa.kernels:
  - .agpr_count:     0
    .args:
      - .offset:         0
        .size:           176
        .value_kind:     by_value
      - .offset:         176
        .size:           4
        .value_kind:     hidden_block_count_x
      - .offset:         180
        .size:           4
        .value_kind:     hidden_block_count_y
      - .offset:         184
        .size:           4
        .value_kind:     hidden_block_count_z
      - .offset:         188
        .size:           2
        .value_kind:     hidden_group_size_x
      - .offset:         190
        .size:           2
        .value_kind:     hidden_group_size_y
      - .offset:         192
        .size:           2
        .value_kind:     hidden_group_size_z
      - .offset:         194
        .size:           2
        .value_kind:     hidden_remainder_x
      - .offset:         196
        .size:           2
        .value_kind:     hidden_remainder_y
      - .offset:         198
        .size:           2
        .value_kind:     hidden_remainder_z
      - .offset:         216
        .size:           8
        .value_kind:     hidden_global_offset_x
      - .offset:         224
        .size:           8
        .value_kind:     hidden_global_offset_y
      - .offset:         232
        .size:           8
        .value_kind:     hidden_global_offset_z
      - .offset:         240
        .size:           2
        .value_kind:     hidden_grid_dims
      - .offset:         296
        .size:           4
        .value_kind:     hidden_dynamic_lds_size
    .group_segment_fixed_size: 0
    .kernarg_segment_align: 8
    .kernarg_segment_size: 432
    .language:       OpenCL C
    .language_version:
      - 2
      - 0
    .max_flat_workgroup_size: 512
    .name:           _Z10hybrid_fwd4Args
    .private_segment_fixed_size: 0
    .sgpr_count:     108
    .sgpr_spill_count: 112
    .symbol:         _Z10hybrid_fwd4Args.kd
    .uniform_work_group_size: 1
    .uses_dynamic_stack: false
    .vgpr_count:     256
    .vgpr_spill_count: 0
    .wavefront_size: 64
